# attention main loops: removed redundant lgkmcnt waits, m0 save/restore, permlane moved to rare rescale path
# speedup vs baseline: 1.0114x; 1.0114x over previous
.LBB0_404:
	v_add_u32_e32 v0, s8, v222
	ds_read_b64_tr_b16 v[194:195], v0 offset:24576
	ds_read_b64_tr_b16 v[196:197], v0 offset:25088
	v_mfma_f32_32x32x16_bf16 v[114:129], v[190:193], v[142:145], v[34:49]
	v_add_f32_e32 v67, v82, v83
	v_add_f32_e32 v67, v84, v67
	v_add_f32_e32 v67, v85, v67
	v_add_f32_e32 v67, v86, v67
	v_add_f32_e32 v67, v87, v67
	v_cvt_pk_bf16_f32 v158, v82, v83
	v_cvt_pk_bf16_f32 v159, v84, v85
	ds_read_b64_tr_b16 v[190:191], v0 offset:28672
	ds_read_b64_tr_b16 v[192:193], v0 offset:29184
	v_mfma_f32_32x32x16_bf16 v[98:113], v[186:189], v[142:145], v[34:49]
	v_add_f32_e32 v67, v88, v67
	v_add_f32_e32 v67, v89, v67
	v_add_f32_e32 v67, v90, v67
	v_add_f32_e32 v67, v91, v67
	v_cvt_pk_bf16_f32 v160, v86, v87
	v_cvt_pk_bf16_f32 v161, v88, v89
	ds_read_b64_tr_b16 v[82:83], v0 offset:25600
	ds_read_b64_tr_b16 v[84:85], v0 offset:26112
	v_mfma_f32_32x32x16_bf16 v[114:129], v[182:185], v[138:141], v[114:129]
	v_add_f32_e32 v67, v92, v67
	v_add_f32_e32 v67, v93, v67
	v_add_f32_e32 v67, v94, v67
	v_add_f32_e32 v67, v95, v67
	v_cvt_pk_bf16_f32 v154, v90, v91
	v_cvt_pk_bf16_f32 v155, v92, v93
	ds_read_b64_tr_b16 v[68:69], v0 offset:29696
	ds_read_b64_tr_b16 v[70:71], v0 offset:30208
	v_mfma_f32_32x32x16_bf16 v[98:113], v[178:181], v[138:141], v[98:113]
	v_add_f32_e32 v67, v96, v67
	v_add_f32_e32 v67, v97, v67
	v_add_f32_e32 v67, v50, v67
	v_add_f32_e32 v67, v51, v67
	v_cvt_pk_bf16_f32 v156, v94, v95
	v_cvt_pk_bf16_f32 v157, v96, v97
	ds_read_b64_tr_b16 v[74:75], v0 offset:26624
	ds_read_b64_tr_b16 v[76:77], v0 offset:27136
	v_mfma_f32_32x32x16_bf16 v[114:129], v[174:177], v[134:137], v[114:129]
	v_add_f32_e32 v67, v52, v67
	v_add_f32_e32 v67, v53, v67
	v_add_f32_e32 v67, v54, v67
	v_add_f32_e32 v67, v55, v67
	v_cvt_pk_bf16_f32 v150, v50, v51
	v_cvt_pk_bf16_f32 v151, v52, v53
	ds_read_b64_tr_b16 v[78:79], v0 offset:30720
	ds_read_b64_tr_b16 v[80:81], v0 offset:31232
	v_mfma_f32_32x32x16_bf16 v[98:113], v[170:173], v[134:137], v[98:113]
	v_add_f32_e32 v50, v56, v67
	v_add_f32_e32 v50, v57, v50
	v_add_f32_e32 v50, v58, v50
	v_add_f32_e32 v50, v59, v50
	v_cvt_pk_bf16_f32 v152, v54, v55
	v_cvt_pk_bf16_f32 v153, v56, v57
	ds_read_b64_tr_b16 v[54:55], v0 offset:27648
	ds_read_b64_tr_b16 v[56:57], v0 offset:28160
	v_mfma_f32_32x32x16_bf16 v[114:129], v[166:169], v[130:133], v[114:129]
	v_add_f32_e32 v50, v60, v50
	v_add_f32_e32 v50, v61, v50
	v_add_f32_e32 v50, v62, v50
	v_add_f32_e32 v67, v63, v50
	v_cvt_pk_bf16_f32 v146, v58, v59
	v_cvt_pk_bf16_f32 v147, v60, v61
	ds_read_b64_tr_b16 v[50:51], v0 offset:31744
	ds_read_b64_tr_b16 v[52:53], v0 offset:32256
	v_mfma_f32_32x32x16_bf16 v[98:113], v[162:165], v[130:133], v[98:113]
	v_add_f32_e32 v0, v64, v67
	v_add_f32_e32 v0, v65, v0
	v_add_f32_e32 v0, 0, v0
	v_cvt_pk_bf16_f32 v148, v62, v63
	v_cvt_pk_bf16_f32 v149, v64, v65
	s_add_i32 m0, s50, s86
	v_lshl_add_u64 v[58:59], v[204:205], 0, s[26:27]
	global_load_lds_dwordx4 v[58:59], off
	s_add_i32 m0, s48, s87
	v_lshl_add_u64 v[58:59], v[202:203], 0, s[26:27]
	global_load_lds_dwordx4 v[58:59], off
	v_max_f32_e32 v58, v114, v115
	v_max3_f32 v59, v116, v117, v99
	v_max3_f32 v58, v58, v98, v100
	v_max3_f32 v58, v58, v101, v118
	v_max3_f32 v59, v59, v120, v121
	v_max3_f32 v58, v58, v119, v102
	v_max3_f32 v59, v59, v104, v105
	v_max3_f32 v58, v58, v103, v122
	v_max3_f32 v59, v59, v124, v125
	v_max3_f32 v58, v58, v123, v106
	v_max3_f32 v59, v59, v108, v109
	v_max3_f32 v58, v58, v107, v126
	v_max3_f32 v59, v59, v128, v129
	v_max3_f32 v58, v58, v127, v110
	v_max3_f32 v59, v59, v112, v113
	v_add_f32_e32 v186, v66, v0
	v_max3_f32 v0, v58, v111, v59
	v_cmp_lt_f32_e32 vcc, s79, v0
	s_mov_b64 s[8:9], 0
	s_cbranch_vccnz .LBB0_414
.LBB0_405:
	s_waitcnt lgkmcnt(0)
	v_mfma_f32_32x32x16_bf16 v[18:33], v[158:161], v[194:197], v[18:33]
	v_exp_f32_e32 v114, v114
	v_exp_f32_e32 v115, v115
	v_exp_f32_e32 v116, v116
	v_exp_f32_e32 v117, v117
	v_mfma_f32_32x32x16_bf16 v[2:17], v[158:161], v[190:193], v[2:17]
	v_exp_f32_e32 v118, v118
	v_exp_f32_e32 v119, v119
	v_exp_f32_e32 v120, v120
	v_exp_f32_e32 v121, v121
	v_add_u32_e32 v0, s48, v221
	ds_read_b128 v[58:61], v0
	ds_read_b128 v[166:169], v0 offset:512
	v_mfma_f32_32x32x16_bf16 v[18:33], v[154:157], v[82:85], v[18:33]
	v_exp_f32_e32 v122, v122
	v_exp_f32_e32 v123, v123
	v_exp_f32_e32 v124, v124
	v_exp_f32_e32 v125, v125
	ds_read_b128 v[182:185], v0 offset:2048
	ds_read_b128 v[162:165], v0 offset:2560
	v_mfma_f32_32x32x16_bf16 v[2:17], v[154:157], v[68:71], v[2:17]
	v_exp_f32_e32 v126, v126
	v_exp_f32_e32 v127, v127
	v_exp_f32_e32 v128, v128
	v_exp_f32_e32 v129, v129
	ds_read_b128 v[170:173], v0 offset:4096
	ds_read_b128 v[70:73], v0 offset:4608
	v_mfma_f32_32x32x16_bf16 v[18:33], v[150:153], v[74:77], v[18:33]
	v_exp_f32_e32 v98, v98
	v_exp_f32_e32 v99, v99
	v_exp_f32_e32 v100, v100
	v_exp_f32_e32 v101, v101
	ds_read_b128 v[74:77], v0 offset:6144
	ds_read_b128 v[66:69], v0 offset:6656
	v_mfma_f32_32x32x16_bf16 v[2:17], v[150:153], v[78:81], v[2:17]
	v_exp_f32_e32 v102, v102
	v_exp_f32_e32 v103, v103
	v_exp_f32_e32 v104, v104
	v_exp_f32_e32 v105, v105
	v_mfma_f32_32x32x16_bf16 v[18:33], v[146:149], v[54:57], v[18:33]
	v_exp_f32_e32 v106, v106
	v_exp_f32_e32 v107, v107
	v_exp_f32_e32 v108, v108
	v_exp_f32_e32 v109, v109
	v_mfma_f32_32x32x16_bf16 v[2:17], v[146:149], v[50:53], v[2:17]
	v_exp_f32_e32 v110, v110
	v_exp_f32_e32 v111, v111
	v_exp_f32_e32 v112, v112
	v_exp_f32_e32 v113, v113
	s_waitcnt vmcnt(2) lgkmcnt(0)
	s_barrier
	s_andn2_b64 vcc, exec, s[8:9]
	v_add_u32_e32 v0, s85, v224
	s_cbranch_vccnz .LBB0_407
	s_waitcnt lgkmcnt(0)
	ds_read_b128 v[50:53], v0 offset:96
	ds_read_b128 v[54:57], v0 offset:64
	ds_read_b128 v[62:65], v0 offset:32
	ds_read_b128 v[78:81], v0
	s_waitcnt lgkmcnt(3)
	v_pk_mul_f32 v[30:31], v[30:31], v[50:51]
	s_waitcnt lgkmcnt(2)
	v_pk_mul_f32 v[26:27], v[26:27], v[54:55]
	s_waitcnt lgkmcnt(1)
	v_pk_mul_f32 v[22:23], v[22:23], v[62:63]
	v_pk_mul_f32 v[32:33], v[32:33], v[52:53]
	v_pk_mul_f32 v[28:29], v[28:29], v[56:57]
	v_pk_mul_f32 v[24:25], v[24:25], v[64:65]
	s_waitcnt lgkmcnt(0)
	v_pk_mul_f32 v[20:21], v[20:21], v[80:81]
	v_pk_mul_f32 v[18:19], v[18:19], v[78:79]
	v_pk_mul_f32 v[14:15], v[14:15], v[50:51]
	v_pk_mul_f32 v[10:11], v[10:11], v[54:55]
	v_pk_mul_f32 v[6:7], v[6:7], v[62:63]
	v_pk_mul_f32 v[16:17], v[16:17], v[52:53]
	v_pk_mul_f32 v[12:13], v[12:13], v[56:57]
	v_pk_mul_f32 v[8:9], v[8:9], v[64:65]
	v_pk_mul_f32 v[4:5], v[4:5], v[80:81]
	v_pk_mul_f32 v[2:3], v[2:3], v[78:79]

.LBB0_409:
	s_add_i32 s8, s48, 0x2000
	s_cmpk_lg_i32 s48, 0x4000
	s_cselect_b32 s89, s8, 0
	v_add_u32_e32 v187, s50, v222
	ds_read_b64_tr_b16 v[178:179], v187 offset:24576
	ds_read_b64_tr_b16 v[180:181], v187 offset:25088
	v_mfma_f32_32x32x16_bf16 v[82:97], v[58:61], v[142:145], v[34:49]
	v_add_f32_e32 v50, v114, v115
	v_add_f32_e32 v50, v116, v50
	v_add_f32_e32 v50, v117, v50
	v_add_f32_e32 v50, v118, v50
	v_add_f32_e32 v50, v119, v50
	v_cvt_pk_bf16_f32 v158, v114, v115
	v_cvt_pk_bf16_f32 v159, v116, v117
	ds_read_b64_tr_b16 v[174:175], v187 offset:28672
	ds_read_b64_tr_b16 v[176:177], v187 offset:29184
	v_add_f32_e32 v50, v120, v50
	v_add_f32_e32 v50, v121, v50
	v_add_f32_e32 v50, v122, v50
	v_add_f32_e32 v78, v123, v50
	v_mfma_f32_32x32x16_bf16 v[50:65], v[166:169], v[142:145], v[34:49]
	v_cvt_pk_bf16_f32 v160, v118, v119
	v_cvt_pk_bf16_f32 v161, v120, v121
	ds_read_b64_tr_b16 v[166:167], v187 offset:25600
	ds_read_b64_tr_b16 v[168:169], v187 offset:26112
	v_mfma_f32_32x32x16_bf16 v[82:97], v[182:185], v[138:141], v[82:97]
	v_add_f32_e32 v78, v124, v78
	v_add_f32_e32 v78, v125, v78
	v_add_f32_e32 v78, v126, v78
	v_add_f32_e32 v78, v127, v78
	v_cvt_pk_bf16_f32 v154, v122, v123
	v_cvt_pk_bf16_f32 v155, v124, v125
	ds_read_b64_tr_b16 v[118:119], v187 offset:29696
	ds_read_b64_tr_b16 v[120:121], v187 offset:30208
	v_mfma_f32_32x32x16_bf16 v[50:65], v[162:165], v[138:141], v[50:65]
	v_add_f32_e32 v78, v128, v78
	v_add_f32_e32 v78, v129, v78
	v_add_f32_e32 v78, v98, v78
	v_add_f32_e32 v78, v99, v78
	v_cvt_pk_bf16_f32 v156, v126, v127
	v_cvt_pk_bf16_f32 v157, v128, v129
	ds_read_b64_tr_b16 v[114:115], v187 offset:26624
	ds_read_b64_tr_b16 v[116:117], v187 offset:27136
	v_mfma_f32_32x32x16_bf16 v[82:97], v[170:173], v[134:137], v[82:97]
	v_add_f32_e32 v78, v100, v78
	v_add_f32_e32 v78, v101, v78
	v_add_f32_e32 v78, v102, v78
	v_add_f32_e32 v78, v103, v78
	v_cvt_pk_bf16_f32 v150, v98, v99
	v_cvt_pk_bf16_f32 v151, v100, v101
	ds_read_b64_tr_b16 v[98:99], v187 offset:30720
	ds_read_b64_tr_b16 v[100:101], v187 offset:31232
	v_mfma_f32_32x32x16_bf16 v[50:65], v[70:73], v[134:137], v[50:65]
	v_add_f32_e32 v78, v104, v78
	v_add_f32_e32 v78, v105, v78
	v_add_f32_e32 v78, v106, v78
	v_add_f32_e32 v122, v107, v78
	v_cvt_pk_bf16_f32 v152, v102, v103
	v_cvt_pk_bf16_f32 v153, v104, v105
	ds_read_b64_tr_b16 v[78:79], v187 offset:27648
	ds_read_b64_tr_b16 v[80:81], v187 offset:28160
	v_mfma_f32_32x32x16_bf16 v[82:97], v[74:77], v[130:133], v[82:97]
	v_add_f32_e32 v70, v108, v122
	v_add_f32_e32 v70, v109, v70
	v_add_f32_e32 v70, v110, v70
	v_add_f32_e32 v102, v111, v70
	v_cvt_pk_bf16_f32 v146, v106, v107
	v_cvt_pk_bf16_f32 v147, v108, v109
	ds_read_b64_tr_b16 v[70:71], v187 offset:31744
	ds_read_b64_tr_b16 v[72:73], v187 offset:32256
	v_mfma_f32_32x32x16_bf16 v[50:65], v[66:69], v[130:133], v[50:65]
	v_add_f32_e32 v74, v112, v102
	v_add_f32_e32 v74, v113, v74
	v_add_f32_e32 v74, 0, v74
	v_cvt_pk_bf16_f32 v148, v110, v111
	v_cvt_pk_bf16_f32 v149, v112, v113
	s_add_i32 m0, s48, s86
	v_max_f32_e32 v66, v82, v83
	global_load_lds_dwordx4 v[204:205], off
	s_add_i32 m0, s89, s87
	s_nop 1
	global_load_lds_dwordx4 v[202:203], off
	v_max3_f32 v67, v84, v85, v51
	v_max3_f32 v66, v66, v50, v52
	v_max3_f32 v66, v66, v53, v86
	v_max3_f32 v67, v67, v88, v89
	v_max3_f32 v66, v66, v87, v54
	v_max3_f32 v67, v67, v56, v57
	v_max3_f32 v66, v66, v55, v90
	v_max3_f32 v67, v67, v92, v93
	v_max3_f32 v66, v66, v91, v58
	v_max3_f32 v67, v67, v60, v61
	v_max3_f32 v66, v66, v59, v94
	v_max3_f32 v67, v67, v96, v97
	v_max3_f32 v68, v66, v95, v62
	v_max3_f32 v67, v67, v64, v65
	v_max3_f32 v67, v68, v63, v67
	v_cmp_lt_f32_e32 vcc, s79, v67
	v_add_f32_e32 v66, v186, v74
	s_mov_b64 s[8:9], 0
	s_cbranch_vccnz .LBB0_417
.LBB0_410:
	s_waitcnt lgkmcnt(0)
	v_mfma_f32_32x32x16_bf16 v[18:33], v[158:161], v[178:181], v[18:33]
	v_exp_f32_e32 v82, v82
	v_exp_f32_e32 v83, v83
	v_exp_f32_e32 v84, v84
	v_exp_f32_e32 v85, v85
	v_mfma_f32_32x32x16_bf16 v[2:17], v[158:161], v[174:177], v[2:17]
	v_exp_f32_e32 v86, v86
	v_exp_f32_e32 v87, v87
	v_exp_f32_e32 v88, v88
	v_exp_f32_e32 v89, v89
	v_add_u32_e32 v67, s89, v221
	ds_read_b128 v[190:193], v67
	ds_read_b128 v[186:189], v67 offset:512
	v_mfma_f32_32x32x16_bf16 v[18:33], v[154:157], v[166:169], v[18:33]
	v_exp_f32_e32 v90, v90
	v_exp_f32_e32 v91, v91
	v_exp_f32_e32 v92, v92
	v_exp_f32_e32 v93, v93
	ds_read_b128 v[182:185], v67 offset:2048
	ds_read_b128 v[178:181], v67 offset:2560
	v_mfma_f32_32x32x16_bf16 v[2:17], v[154:157], v[118:121], v[2:17]
	v_exp_f32_e32 v94, v94
	v_exp_f32_e32 v95, v95
	v_exp_f32_e32 v96, v96
	v_exp_f32_e32 v97, v97
	ds_read_b128 v[174:177], v67 offset:4096
	ds_read_b128 v[170:173], v67 offset:4608
	v_mfma_f32_32x32x16_bf16 v[18:33], v[150:153], v[114:117], v[18:33]
	v_exp_f32_e32 v50, v50
	v_exp_f32_e32 v51, v51
	v_exp_f32_e32 v52, v52
	v_exp_f32_e32 v53, v53
	ds_read_b128 v[166:169], v67 offset:6144
	ds_read_b128 v[162:165], v67 offset:6656
	v_mfma_f32_32x32x16_bf16 v[2:17], v[150:153], v[98:101], v[2:17]
	v_exp_f32_e32 v54, v54
	v_exp_f32_e32 v55, v55
	v_exp_f32_e32 v56, v56
	v_exp_f32_e32 v57, v57
	v_mfma_f32_32x32x16_bf16 v[18:33], v[146:149], v[78:81], v[18:33]
	v_exp_f32_e32 v58, v58
	v_exp_f32_e32 v59, v59
	v_exp_f32_e32 v60, v60
	v_exp_f32_e32 v61, v61
	v_mfma_f32_32x32x16_bf16 v[2:17], v[146:149], v[70:73], v[2:17]
	v_exp_f32_e32 v62, v62
	v_exp_f32_e32 v63, v63
	v_exp_f32_e32 v64, v64
	v_exp_f32_e32 v65, v65
	s_waitcnt vmcnt(2) lgkmcnt(0)
	s_barrier
	s_andn2_b64 vcc, exec, s[8:9]
	s_cbranch_vccnz .LBB0_412
	s_waitcnt lgkmcnt(0)
	ds_read_b128 v[68:71], v0 offset:96
	ds_read_b128 v[72:75], v0 offset:64
	ds_read_b128 v[76:79], v0 offset:32
	ds_read_b128 v[98:101], v0
	s_waitcnt lgkmcnt(3)
	v_pk_mul_f32 v[30:31], v[30:31], v[68:69]
	s_waitcnt lgkmcnt(2)
	v_pk_mul_f32 v[26:27], v[26:27], v[72:73]
	s_waitcnt lgkmcnt(1)
	v_pk_mul_f32 v[22:23], v[22:23], v[76:77]
	v_pk_mul_f32 v[32:33], v[32:33], v[70:71]
	v_pk_mul_f32 v[28:29], v[28:29], v[74:75]
	v_pk_mul_f32 v[24:25], v[24:25], v[78:79]
	s_waitcnt lgkmcnt(0)
	v_pk_mul_f32 v[20:21], v[20:21], v[100:101]
	v_pk_mul_f32 v[18:19], v[18:19], v[98:99]
	v_pk_mul_f32 v[14:15], v[14:15], v[68:69]
	v_pk_mul_f32 v[10:11], v[10:11], v[72:73]
	v_pk_mul_f32 v[6:7], v[6:7], v[76:77]
	v_pk_mul_f32 v[16:17], v[16:17], v[70:71]
	v_pk_mul_f32 v[12:13], v[12:13], v[74:75]
	v_pk_mul_f32 v[8:9], v[8:9], v[78:79]
	v_pk_mul_f32 v[4:5], v[4:5], v[100:101]
	v_pk_mul_f32 v[2:3], v[2:3], v[98:99]

.LBB0_414:
	v_mov_b32_e32 v58, v0
	s_mov_b64 s[8:9], -1
	s_nop 0
	v_permlane32_swap_b32_e32 v0, v58
	v_max_f32_e32 v0, v0, v58
	v_max_f32_e32 v0, v0, v0
	v_max_f32_e32 v0, 0, v0
	v_exp_f32_e64 v58, -v0
	v_add_f32_e32 v220, v220, v0
	v_cndmask_b32_e64 v34, v236, -v220, s[44:45]
	v_mov_b32_e32 v35, v34
	v_mov_b32_e32 v36, v34
	v_mov_b32_e32 v37, v34
	v_mov_b32_e32 v38, v34
	v_mov_b32_e32 v39, v34
	v_mov_b32_e32 v40, v34
	v_mov_b32_e32 v41, v34
	v_mov_b32_e32 v42, v34
	v_mov_b32_e32 v43, v34
	v_mov_b32_e32 v44, v34
	v_mov_b32_e32 v45, v34
	v_mov_b32_e32 v46, v34
	v_mov_b32_e32 v47, v34
	v_mov_b32_e32 v48, v34
	v_mov_b32_e32 v49, v34
	s_and_saveexec_b64 s[46:47], s[6:7]
	ds_write_b32 v218, v58
	s_or_b64 exec, exec, s[46:47]
	v_sub_f32_e32 v129, v129, v0
	v_sub_f32_e32 v128, v128, v0
	v_sub_f32_e32 v127, v127, v0
	v_sub_f32_e32 v126, v126, v0
	v_sub_f32_e32 v125, v125, v0
	v_sub_f32_e32 v124, v124, v0
	v_sub_f32_e32 v123, v123, v0
	v_sub_f32_e32 v122, v122, v0
	v_sub_f32_e32 v121, v121, v0
	v_sub_f32_e32 v120, v120, v0
	v_sub_f32_e32 v119, v119, v0
	v_sub_f32_e32 v118, v118, v0
	v_sub_f32_e32 v117, v117, v0
	v_sub_f32_e32 v116, v116, v0
	v_sub_f32_e32 v115, v115, v0
	v_sub_f32_e32 v114, v114, v0
	v_sub_f32_e32 v113, v113, v0
	v_sub_f32_e32 v112, v112, v0
	v_sub_f32_e32 v111, v111, v0
	v_sub_f32_e32 v110, v110, v0
	v_sub_f32_e32 v109, v109, v0
	v_sub_f32_e32 v108, v108, v0
	v_sub_f32_e32 v107, v107, v0
	v_sub_f32_e32 v106, v106, v0
	v_sub_f32_e32 v105, v105, v0
	v_sub_f32_e32 v104, v104, v0
	v_sub_f32_e32 v103, v103, v0
	v_sub_f32_e32 v102, v102, v0
	v_sub_f32_e32 v101, v101, v0
	v_sub_f32_e32 v100, v100, v0
	v_sub_f32_e32 v99, v99, v0
	v_sub_f32_e32 v98, v98, v0
	v_mul_f32_e32 v186, v186, v58
	s_branch .LBB0_405
.LBB0_417:
	v_mov_b32_e32 v68, v67
	s_mov_b64 s[8:9], -1
	s_nop 0
	v_permlane32_swap_b32_e32 v67, v68
	v_max_f32_e32 v67, v67, v68
	v_max_f32_e32 v34, v67, v67
	v_max_f32_e32 v67, 0, v34
	v_exp_f32_e64 v68, -v67
	v_add_f32_e32 v220, v220, v67
	v_cndmask_b32_e64 v34, v236, -v220, s[44:45]
	v_mov_b32_e32 v35, v34
	v_mov_b32_e32 v36, v34
	v_mov_b32_e32 v37, v34
	v_mov_b32_e32 v38, v34
	v_mov_b32_e32 v39, v34
	v_mov_b32_e32 v40, v34
	v_mov_b32_e32 v41, v34
	v_mov_b32_e32 v42, v34
	v_mov_b32_e32 v43, v34
	v_mov_b32_e32 v44, v34
	v_mov_b32_e32 v45, v34
	v_mov_b32_e32 v46, v34
	v_mov_b32_e32 v47, v34
	v_mov_b32_e32 v48, v34
	v_mov_b32_e32 v49, v34
	s_and_saveexec_b64 s[46:47], s[6:7]
	ds_write_b32 v218, v68
	s_or_b64 exec, exec, s[46:47]
	v_sub_f32_e32 v97, v97, v67
	v_sub_f32_e32 v96, v96, v67
	v_sub_f32_e32 v95, v95, v67
	v_sub_f32_e32 v94, v94, v67
	v_sub_f32_e32 v93, v93, v67
	v_sub_f32_e32 v92, v92, v67
	v_sub_f32_e32 v91, v91, v67
	v_sub_f32_e32 v90, v90, v67
	v_sub_f32_e32 v89, v89, v67
	v_sub_f32_e32 v88, v88, v67
	v_sub_f32_e32 v87, v87, v67
	v_sub_f32_e32 v86, v86, v67
	v_sub_f32_e32 v85, v85, v67
	v_sub_f32_e32 v84, v84, v67
	v_sub_f32_e32 v83, v83, v67
	v_sub_f32_e32 v82, v82, v67
	v_sub_f32_e32 v65, v65, v67
	v_sub_f32_e32 v64, v64, v67
	v_sub_f32_e32 v63, v63, v67
	v_sub_f32_e32 v62, v62, v67
	v_sub_f32_e32 v61, v61, v67
	v_sub_f32_e32 v60, v60, v67
	v_sub_f32_e32 v59, v59, v67
	v_sub_f32_e32 v58, v58, v67
	v_sub_f32_e32 v57, v57, v67
	v_sub_f32_e32 v56, v56, v67
	v_sub_f32_e32 v55, v55, v67
	v_sub_f32_e32 v54, v54, v67
	v_sub_f32_e32 v53, v53, v67
	v_sub_f32_e32 v52, v52, v67
	v_sub_f32_e32 v51, v51, v67
	v_sub_f32_e32 v50, v50, v67
	v_mul_f32_e32 v66, v66, v68
	s_branch .LBB0_410

.LBB0_484:
	v_add_u32_e32 v0, s38, v249
	ds_read_b64_tr_b16 v[10:11], v0 offset:24576
	ds_read_b64_tr_b16 v[12:13], v0 offset:25088
	v_mfma_f32_32x32x16_bf16 v[144:159], v[220:223], v[188:191], v[80:95]
	v_add_f32_e32 v2, v112, v113
	v_add_f32_e32 v2, v114, v2
	v_add_f32_e32 v2, v115, v2
	v_add_f32_e32 v2, v116, v2
	v_add_f32_e32 v2, v117, v2
	v_cvt_pk_bf16_f32 v184, v112, v113
	v_cvt_pk_bf16_f32 v185, v114, v115
	ds_read_b64_tr_b16 v[112:113], v0 offset:28672
	ds_read_b64_tr_b16 v[114:115], v0 offset:29184
	v_mfma_f32_32x32x16_bf16 v[128:143], v[216:219], v[188:191], v[80:95]
	v_add_f32_e32 v2, v118, v2
	v_add_f32_e32 v2, v119, v2
	v_add_f32_e32 v2, v120, v2
	v_add_f32_e32 v2, v121, v2
	v_cvt_pk_bf16_f32 v186, v116, v117
	v_cvt_pk_bf16_f32 v187, v118, v119
	ds_read_b64_tr_b16 v[6:7], v0 offset:25600
	ds_read_b64_tr_b16 v[8:9], v0 offset:26112
	v_mfma_f32_32x32x16_bf16 v[144:159], v[212:215], v[180:183], v[144:159]
	v_add_f32_e32 v2, v122, v2
	v_add_f32_e32 v2, v123, v2
	v_add_f32_e32 v2, v124, v2
	v_add_f32_e32 v14, v125, v2
	v_cvt_pk_bf16_f32 v176, v120, v121
	v_cvt_pk_bf16_f32 v177, v122, v123
	ds_read_b64_tr_b16 v[2:3], v0 offset:29696
	ds_read_b64_tr_b16 v[4:5], v0 offset:30208
	v_mfma_f32_32x32x16_bf16 v[128:143], v[208:211], v[180:183], v[128:143]
	v_add_f32_e32 v14, v126, v14
	v_add_f32_e32 v14, v127, v14
	v_add_f32_e32 v14, v96, v14
	v_add_f32_e32 v14, v97, v14
	v_cvt_pk_bf16_f32 v178, v124, v125
	v_cvt_pk_bf16_f32 v179, v126, v127
	v_mfma_f32_32x32x16_bf16 v[144:159], v[204:207], v[172:175], v[144:159]
	v_add_f32_e32 v14, v98, v14
	v_add_f32_e32 v14, v99, v14
	v_add_f32_e32 v14, v100, v14
	v_add_f32_e32 v14, v101, v14
	v_cvt_pk_bf16_f32 v164, v96, v97
	v_cvt_pk_bf16_f32 v165, v98, v99
	v_mfma_f32_32x32x16_bf16 v[128:143], v[200:203], v[172:175], v[128:143]
	v_add_f32_e32 v14, v102, v14
	v_add_f32_e32 v14, v103, v14
	v_add_f32_e32 v14, v104, v14
	v_add_f32_e32 v14, v105, v14
	v_cvt_pk_bf16_f32 v166, v100, v101
	v_cvt_pk_bf16_f32 v167, v102, v103
	v_mfma_f32_32x32x16_bf16 v[144:159], v[196:199], v[168:171], v[144:159]
	v_add_f32_e32 v14, v106, v14
	v_add_f32_e32 v14, v107, v14
	v_add_f32_e32 v14, v108, v14
	v_add_f32_e32 v14, v109, v14
	v_cvt_pk_bf16_f32 v160, v104, v105
	v_cvt_pk_bf16_f32 v161, v106, v107
	v_mfma_f32_32x32x16_bf16 v[128:143], v[192:195], v[168:171], v[128:143]
	v_add_f32_e32 v14, v110, v14
	v_add_f32_e32 v14, v111, v14
	v_add_f32_e32 v96, 0, v14
	v_cvt_pk_bf16_f32 v162, v108, v109
	v_cvt_pk_bf16_f32 v163, v110, v111
	s_add_i32 m0, s44, s53
	v_lshl_add_u64 v[14:15], v[234:235], 0, s[26:27]
	global_load_lds_dwordx4 v[14:15], off
	s_add_i32 m0, s42, s83
	v_lshl_add_u64 v[14:15], v[232:233], 0, s[26:27]
	global_load_lds_dwordx4 v[14:15], off
	s_add_i32 m0, s42, s84
	v_lshl_add_u64 v[14:15], v[230:231], 0, s[26:27]
	global_load_lds_dwordx4 v[14:15], off
	v_max_f32_e32 v14, v144, v145
	v_max3_f32 v15, v146, v147, v129
	v_max3_f32 v14, v14, v128, v130
	v_max3_f32 v14, v14, v131, v148
	v_max3_f32 v15, v15, v150, v151
	v_max3_f32 v14, v14, v149, v132
	v_max3_f32 v15, v15, v134, v135
	v_max3_f32 v14, v14, v133, v152
	v_max3_f32 v15, v15, v154, v155
	v_max3_f32 v14, v14, v153, v136
	v_max3_f32 v15, v15, v138, v139
	v_max3_f32 v14, v14, v137, v156
	v_max3_f32 v15, v15, v158, v159
	v_max3_f32 v97, v14, v157, v140
	v_max3_f32 v15, v15, v142, v143
	v_max3_f32 v15, v97, v141, v15
	v_add_f32_e32 v14, v251, v96
	v_cmp_lt_f32_e32 vcc, s79, v15
	s_mov_b64 s[38:39], 0
	s_cbranch_vccnz .LBB0_492

.LBB0_487:
	s_add_i32 s38, s42, 0x2000
	s_cmpk_lg_i32 s42, 0x4000
	s_cselect_b32 s86, s38, 0
	v_add_u32_e32 v15, s44, v249
	ds_read_b64_tr_b16 v[208:209], v15 offset:24576
	ds_read_b64_tr_b16 v[210:211], v15 offset:25088
	v_mfma_f32_32x32x16_bf16 v[112:127], v[96:99], v[188:191], v[80:95]
	v_add_f32_e32 v100, v144, v145
	v_add_f32_e32 v100, v146, v100
	v_add_f32_e32 v100, v147, v100
	v_add_f32_e32 v100, v148, v100
	v_add_f32_e32 v100, v149, v100
	v_cvt_pk_bf16_f32 v184, v144, v145
	v_cvt_pk_bf16_f32 v185, v146, v147
	ds_read_b64_tr_b16 v[212:213], v15 offset:28672
	ds_read_b64_tr_b16 v[214:215], v15 offset:29184
	v_add_f32_e32 v96, v150, v100
	v_add_f32_e32 v96, v151, v96
	v_add_f32_e32 v96, v152, v96
	v_add_f32_e32 v144, v153, v96
	v_mfma_f32_32x32x16_bf16 v[96:111], v[200:203], v[188:191], v[80:95]
	v_cvt_pk_bf16_f32 v186, v148, v149
	v_cvt_pk_bf16_f32 v187, v150, v151
	ds_read_b64_tr_b16 v[148:149], v15 offset:25600
	ds_read_b64_tr_b16 v[150:151], v15 offset:26112
	v_mfma_f32_32x32x16_bf16 v[112:127], v[204:207], v[180:183], v[112:127]
	v_add_f32_e32 v144, v154, v144
	v_add_f32_e32 v144, v155, v144
	v_add_f32_e32 v144, v156, v144
	v_add_f32_e32 v160, v157, v144
	v_cvt_pk_bf16_f32 v176, v152, v153
	v_cvt_pk_bf16_f32 v177, v154, v155
	ds_read_b64_tr_b16 v[144:145], v15 offset:29696
	ds_read_b64_tr_b16 v[146:147], v15 offset:30208
	v_mfma_f32_32x32x16_bf16 v[96:111], v[192:195], v[180:183], v[96:111]
	v_add_f32_e32 v152, v158, v160
	v_add_f32_e32 v152, v159, v152
	v_add_f32_e32 v152, v128, v152
	v_add_f32_e32 v152, v129, v152
	v_cvt_pk_bf16_f32 v178, v156, v157
	v_cvt_pk_bf16_f32 v179, v158, v159
	v_mfma_f32_32x32x16_bf16 v[112:127], v[196:199], v[172:175], v[112:127]
	v_add_f32_e32 v152, v130, v152
	v_add_f32_e32 v152, v131, v152
	v_add_f32_e32 v152, v132, v152
	v_add_f32_e32 v152, v133, v152
	v_cvt_pk_bf16_f32 v164, v128, v129
	v_cvt_pk_bf16_f32 v165, v130, v131
	v_mfma_f32_32x32x16_bf16 v[96:111], v[6:9], v[172:175], v[96:111]
	v_add_f32_e32 v128, v134, v152
	v_add_f32_e32 v128, v135, v128
	v_add_f32_e32 v128, v136, v128
	v_add_f32_e32 v128, v137, v128
	v_cvt_pk_bf16_f32 v166, v132, v133
	v_cvt_pk_bf16_f32 v167, v134, v135
	v_mfma_f32_32x32x16_bf16 v[112:127], v[10:13], v[168:171], v[112:127]
	v_add_f32_e32 v6, v138, v128
	v_add_f32_e32 v6, v139, v6
	v_add_f32_e32 v6, v140, v6
	v_add_f32_e32 v6, v141, v6
	v_cvt_pk_bf16_f32 v160, v136, v137
	v_cvt_pk_bf16_f32 v161, v138, v139
	v_mfma_f32_32x32x16_bf16 v[96:111], v[2:5], v[168:171], v[96:111]
	v_add_f32_e32 v6, v142, v6
	v_add_f32_e32 v6, v143, v6
	v_add_f32_e32 v6, 0, v6
	v_cvt_pk_bf16_f32 v162, v140, v141
	v_cvt_pk_bf16_f32 v163, v142, v143
	s_add_i32 m0, s42, s53
	v_max_f32_e32 v2, v112, v113
	global_load_lds_dwordx4 v[234:235], off
	s_add_i32 m0, s86, s83
	s_nop 0
	global_load_lds_dwordx4 v[232:233], off
	s_add_i32 m0, s86, s84
	v_max3_f32 v3, v114, v115, v97
	global_load_lds_dwordx4 v[230:231], off
	v_max3_f32 v2, v2, v96, v98
	v_max3_f32 v2, v2, v99, v116
	v_max3_f32 v3, v3, v118, v119
	v_max3_f32 v2, v2, v117, v100
	v_max3_f32 v3, v3, v102, v103
	v_max3_f32 v2, v2, v101, v120
	v_max3_f32 v3, v3, v122, v123
	v_max3_f32 v2, v2, v121, v104
	v_max3_f32 v3, v3, v106, v107
	v_max3_f32 v2, v2, v105, v124
	v_max3_f32 v3, v3, v126, v127
	v_max3_f32 v2, v2, v125, v108
	v_max3_f32 v3, v3, v110, v111
	v_max3_f32 v2, v2, v109, v3
	v_cmp_lt_f32_e32 vcc, s79, v2
	v_add_f32_e32 v251, v14, v6
	s_mov_b64 s[38:39], 0
	s_cbranch_vccnz .LBB0_495

.LBB0_492:
	v_mov_b32_e32 v96, v15
	s_mov_b64 s[38:39], -1
	s_nop 0
	v_permlane32_swap_b32_e32 v15, v96
	v_max_f32_e32 v15, v15, v96
	v_max_f32_e32 v15, v15, v15
	v_max_f32_e32 v15, 0, v15
	v_exp_f32_e64 v96, -v15
	v_add_f32_e32 v247, v247, v15
	v_xor_b32_e32 v80, 0x80000000, v247
	v_mov_b32_e32 v81, v80
	v_mov_b32_e32 v82, v80
	v_mov_b32_e32 v83, v80
	v_mov_b32_e32 v84, v80
	v_mov_b32_e32 v85, v80
	v_mov_b32_e32 v86, v80
	v_mov_b32_e32 v87, v80
	v_mov_b32_e32 v88, v80
	v_mov_b32_e32 v89, v80
	v_mov_b32_e32 v90, v80
	v_mov_b32_e32 v91, v80
	v_mov_b32_e32 v92, v80
	v_mov_b32_e32 v93, v80
	v_mov_b32_e32 v94, v80
	v_mov_b32_e32 v95, v80
	s_and_saveexec_b64 s[40:41], s[6:7]
	ds_write_b32 v243, v96
	s_or_b64 exec, exec, s[40:41]
	v_sub_f32_e32 v159, v159, v15
	v_sub_f32_e32 v158, v158, v15
	v_sub_f32_e32 v157, v157, v15
	v_sub_f32_e32 v156, v156, v15
	v_sub_f32_e32 v155, v155, v15
	v_sub_f32_e32 v154, v154, v15
	v_sub_f32_e32 v153, v153, v15
	v_sub_f32_e32 v152, v152, v15
	v_sub_f32_e32 v151, v151, v15
	v_sub_f32_e32 v150, v150, v15
	v_sub_f32_e32 v149, v149, v15
	v_sub_f32_e32 v148, v148, v15
	v_sub_f32_e32 v147, v147, v15
	v_sub_f32_e32 v146, v146, v15
	v_sub_f32_e32 v145, v145, v15
	v_sub_f32_e32 v144, v144, v15
	v_sub_f32_e32 v143, v143, v15
	v_sub_f32_e32 v142, v142, v15
	v_sub_f32_e32 v141, v141, v15
	v_sub_f32_e32 v140, v140, v15
	v_sub_f32_e32 v139, v139, v15
	v_sub_f32_e32 v138, v138, v15
	v_sub_f32_e32 v137, v137, v15
	v_sub_f32_e32 v136, v136, v15
	v_sub_f32_e32 v135, v135, v15
	v_sub_f32_e32 v134, v134, v15
	v_sub_f32_e32 v133, v133, v15
	v_sub_f32_e32 v132, v132, v15
	v_sub_f32_e32 v131, v131, v15
	v_sub_f32_e32 v130, v130, v15
	v_sub_f32_e32 v129, v129, v15
	v_sub_f32_e32 v128, v128, v15
	v_mul_f32_e32 v14, v14, v96
	s_branch .LBB0_485
.LBB0_495:
	v_mov_b32_e32 v3, v2
	s_mov_b64 s[38:39], -1
	s_nop 0
	v_permlane32_swap_b32_e32 v2, v3
	v_max_f32_e32 v2, v2, v3
	v_max_f32_e32 v2, v2, v2
	v_max_f32_e32 v2, 0, v2
	v_exp_f32_e64 v3, -v2
	v_add_f32_e32 v247, v247, v2
	v_xor_b32_e32 v80, 0x80000000, v247
	v_mov_b32_e32 v81, v80
	v_mov_b32_e32 v82, v80
	v_mov_b32_e32 v83, v80
	v_mov_b32_e32 v84, v80
	v_mov_b32_e32 v85, v80
	v_mov_b32_e32 v86, v80
	v_mov_b32_e32 v87, v80
	v_mov_b32_e32 v88, v80
	v_mov_b32_e32 v89, v80
	v_mov_b32_e32 v90, v80
	v_mov_b32_e32 v91, v80
	v_mov_b32_e32 v92, v80
	v_mov_b32_e32 v93, v80
	v_mov_b32_e32 v94, v80
	v_mov_b32_e32 v95, v80
	s_and_saveexec_b64 s[40:41], s[6:7]
	ds_write_b32 v243, v3
	s_or_b64 exec, exec, s[40:41]
	v_sub_f32_e32 v127, v127, v2
	v_sub_f32_e32 v126, v126, v2
	v_sub_f32_e32 v125, v125, v2
	v_sub_f32_e32 v124, v124, v2
	v_sub_f32_e32 v123, v123, v2
	v_sub_f32_e32 v122, v122, v2
	v_sub_f32_e32 v121, v121, v2
	v_sub_f32_e32 v120, v120, v2
	v_sub_f32_e32 v119, v119, v2
	v_sub_f32_e32 v118, v118, v2
	v_sub_f32_e32 v117, v117, v2
	v_sub_f32_e32 v116, v116, v2
	v_sub_f32_e32 v115, v115, v2
	v_sub_f32_e32 v114, v114, v2
	v_sub_f32_e32 v113, v113, v2
	v_sub_f32_e32 v112, v112, v2
	v_sub_f32_e32 v111, v111, v2
	v_sub_f32_e32 v110, v110, v2
	v_sub_f32_e32 v109, v109, v2
	v_sub_f32_e32 v108, v108, v2
	v_sub_f32_e32 v107, v107, v2
	v_sub_f32_e32 v106, v106, v2
	v_sub_f32_e32 v105, v105, v2
	v_sub_f32_e32 v104, v104, v2
	v_sub_f32_e32 v103, v103, v2
	v_sub_f32_e32 v102, v102, v2
	v_sub_f32_e32 v101, v101, v2
	v_sub_f32_e32 v100, v100, v2
	v_sub_f32_e32 v99, v99, v2
	v_sub_f32_e32 v98, v98, v2
	v_sub_f32_e32 v97, v97, v2
	v_sub_f32_e32 v96, v96, v2
	v_mul_f32_e32 v251, v251, v3
	s_branch .LBB0_488
